# MLA loop: QK K-fragment reads pipelined 5 deep + PV V-fragment reads double-buffered with group-0 prefetch under softmax (counted lgkmcnt)
# speedup vs baseline: 1.0036x; 1.0036x over previous
.LBB0_542:
	v_add_f32_e32 v117, v100, v101
	v_fmac_f32_e32 v117, v222, v116
	ds_read_b64_tr_b16 v[100:101], v221 offset:0x4200
	ds_read_b64_tr_b16 v[102:103], v221 offset:0x4a00
	ds_read_b64_tr_b16 v[104:105], v221 offset:0x5200
	ds_read_b64_tr_b16 v[106:107], v221 offset:0x5a00
	ds_read_b64_tr_b16 v[108:109], v221 offset:0x6200
	ds_read_b64_tr_b16 v[110:111], v221 offset:0x6a00
	ds_read_b64_tr_b16 v[112:113], v221 offset:0x7200
	ds_read_b64_tr_b16 v[114:115], v221 offset:0x7a00
	s_waitcnt lgkmcnt(8)
	s_nop 0
	v_mfma_f32_32x32x16_bf16 v[4:19], v[88:91], v[236:239], v[4:19]
	v_mfma_f32_32x32x16_bf16 v[4:19], v[92:95], v[240:243], v[4:19]
	v_mfma_f32_32x32x16_bf16 v[4:19], v[96:99], v[244:247], v[4:19]
	v_mfma_f32_32x32x16_bf16 v[4:19], v[84:87], v[248:251], v[4:19]
	ds_read_b64_tr_b16 v[236:237], v221 offset:0x4400
	ds_read_b64_tr_b16 v[238:239], v221 offset:0x4c00
	ds_read_b64_tr_b16 v[240:241], v221 offset:0x5400
	ds_read_b64_tr_b16 v[242:243], v221 offset:0x5c00
	ds_read_b64_tr_b16 v[244:245], v221 offset:0x6400
	ds_read_b64_tr_b16 v[246:247], v221 offset:0x6c00
	ds_read_b64_tr_b16 v[248:249], v221 offset:0x7400
	ds_read_b64_tr_b16 v[250:251], v221 offset:0x7c00
	s_waitcnt lgkmcnt(8)
	v_mfma_f32_32x32x16_bf16 v[52:67], v[88:91], v[100:103], v[52:67]
	v_mfma_f32_32x32x16_bf16 v[52:67], v[92:95], v[104:107], v[52:67]
	v_mfma_f32_32x32x16_bf16 v[52:67], v[96:99], v[108:111], v[52:67]
	v_mfma_f32_32x32x16_bf16 v[52:67], v[84:87], v[112:115], v[52:67]
	ds_read_b64_tr_b16 v[100:101], v221 offset:0x4600
	ds_read_b64_tr_b16 v[102:103], v221 offset:0x4e00
	ds_read_b64_tr_b16 v[104:105], v221 offset:0x5600
	ds_read_b64_tr_b16 v[106:107], v221 offset:0x5e00
	ds_read_b64_tr_b16 v[108:109], v221 offset:0x6600
	ds_read_b64_tr_b16 v[110:111], v221 offset:0x6e00
	ds_read_b64_tr_b16 v[112:113], v221 offset:0x7600
	ds_read_b64_tr_b16 v[114:115], v221 offset:0x7e00
	s_waitcnt lgkmcnt(8)
	v_mfma_f32_32x32x16_bf16 v[20:35], v[88:91], v[236:239], v[20:35]
	v_mfma_f32_32x32x16_bf16 v[20:35], v[92:95], v[240:243], v[20:35]
	v_mfma_f32_32x32x16_bf16 v[20:35], v[96:99], v[244:247], v[20:35]
	v_mfma_f32_32x32x16_bf16 v[20:35], v[84:87], v[248:251], v[20:35]
	s_waitcnt lgkmcnt(0)
	v_mfma_f32_32x32x16_bf16 v[36:51], v[88:91], v[100:103], v[36:51]
	v_mov_b32_e32 v222, v117
	v_mfma_f32_32x32x16_bf16 v[36:51], v[92:95], v[104:107], v[36:51]
	v_mfma_f32_32x32x16_bf16 v[36:51], v[96:99], v[108:111], v[36:51]
	v_mfma_f32_32x32x16_bf16 v[36:51], v[84:87], v[112:115], v[36:51]

.LBB0_544:
	v_lshl_add_u64 v[198:199], s[42:43], 0, v[190:191]
	v_lshl_add_u64 v[84:85], v[198:199], 0, s[94:95]
	s_add_i32 m0, s21, 0x4000
	v_lshl_add_u64 v[200:201], s[42:43], 0, v[192:193]
	global_load_lds_dwordx4 v[84:85], off
	v_lshl_add_u64 v[84:85], v[200:201], 0, s[94:95]
	s_mov_b32 m0, s54
	v_lshl_add_u64 v[202:203], s[42:43], 0, v[194:195]
	global_load_lds_dwordx4 v[84:85], off
	v_lshl_add_u64 v[84:85], v[202:203], 0, s[96:97]
	s_add_i32 m0, s21, 0xc000
	v_lshl_add_u64 v[204:205], s[42:43], 0, v[196:197]
	global_load_lds_dwordx4 v[84:85], off
	v_lshl_add_u64 v[84:85], v[204:205], 0, s[96:97]
	s_mov_b32 m0, s55
	v_lshl_add_u64 v[206:207], s[42:43], 0, v[188:189]
	s_mov_b64 s[10:11], 0x2e602000
	global_load_lds_dwordx4 v[84:85], off
	v_lshl_add_u64 v[84:85], v[206:207], 0, s[10:11]
	s_mov_b32 m0, s52
	s_nop 0
	global_load_lds_dwordx4 v[84:85], off
	s_sub_i32 s3, s24, 63
	s_cmp_gt_i32 s3, s14
	s_cbranch_scc1 .LBB0_552
	s_cmp_le_i32 s24, s6
	v_add_u32_e32 v180, v226, v225
	v_xad_u32 v181, v225, 32, v226
	v_xad_u32 v182, v225, 64, v226
	ds_read_b128 v[84:87], v180 offset:32768
	ds_read_b128 v[236:239], v180 offset:40960
	ds_read_b128 v[240:243], v181 offset:32768
	ds_read_b128 v[244:247], v181 offset:40960
	ds_read_b128 v[248:251], v182 offset:32768
	s_waitcnt lgkmcnt(4)
	v_mfma_f32_32x32x16_bf16 v[100:115], v[84:87], v[176:179], v[68:83]
	ds_read_b128 v[84:87], v182 offset:40960
	v_xad_u32 v183, v225, s26, v226
	s_waitcnt lgkmcnt(4)
	v_mfma_f32_32x32x16_bf16 v[116:131], v[236:239], v[176:179], v[68:83]
	ds_read_b128 v[236:239], v183 offset:32768
	s_waitcnt lgkmcnt(4)
	v_mfma_f32_32x32x16_bf16 v[100:115], v[240:243], v[172:175], v[100:115]
	ds_read_b128 v[240:243], v183 offset:40960
	v_xad_u32 v180, v225, s57, v226
	s_waitcnt lgkmcnt(4)
	v_mfma_f32_32x32x16_bf16 v[116:131], v[244:247], v[172:175], v[116:131]
	ds_read_b128 v[244:247], v180 offset:32768
	s_waitcnt lgkmcnt(4)
	v_mfma_f32_32x32x16_bf16 v[100:115], v[248:251], v[168:171], v[100:115]
	ds_read_b128 v[248:251], v180 offset:40960
	v_xad_u32 v181, v225, s90, v226
	s_waitcnt lgkmcnt(4)
	v_mfma_f32_32x32x16_bf16 v[116:131], v[84:87], v[168:171], v[116:131]
	ds_read_b128 v[84:87], v181 offset:32768
	s_waitcnt lgkmcnt(4)
	v_mfma_f32_32x32x16_bf16 v[100:115], v[236:239], v[164:167], v[100:115]
	ds_read_b128 v[236:239], v181 offset:40960
	v_xad_u32 v182, v225, s56, v226
	s_waitcnt lgkmcnt(4)
	v_mfma_f32_32x32x16_bf16 v[116:131], v[240:243], v[164:167], v[116:131]
	ds_read_b128 v[240:243], v182 offset:32768
	s_waitcnt lgkmcnt(4)
	v_mfma_f32_32x32x16_bf16 v[100:115], v[244:247], v[160:163], v[100:115]
	ds_read_b128 v[244:247], v182 offset:40960
	v_xad_u32 v183, v225, s74, v226
	s_waitcnt lgkmcnt(4)
	v_mfma_f32_32x32x16_bf16 v[116:131], v[248:251], v[160:163], v[116:131]
	ds_read_b128 v[248:251], v183 offset:32768
	s_waitcnt lgkmcnt(4)
	v_mfma_f32_32x32x16_bf16 v[100:115], v[84:87], v[156:159], v[100:115]
	ds_read_b128 v[84:87], v183 offset:40960
	v_add_u32_e32 v180, v227, v228
	s_waitcnt lgkmcnt(4)
	v_mfma_f32_32x32x16_bf16 v[116:131], v[236:239], v[156:159], v[116:131]
	ds_read_b128 v[236:239], v180
	s_waitcnt lgkmcnt(4)
	v_mfma_f32_32x32x16_bf16 v[100:115], v[240:243], v[152:155], v[100:115]
	ds_read_b128 v[240:243], v180 offset:4096
	v_add_u32_e32 v181, v227, v229
	s_waitcnt lgkmcnt(4)
	v_mfma_f32_32x32x16_bf16 v[116:131], v[244:247], v[152:155], v[116:131]
	ds_read_b128 v[244:247], v181
	s_waitcnt lgkmcnt(4)
	v_mfma_f32_32x32x16_bf16 v[100:115], v[248:251], v[148:151], v[100:115]
	ds_read_b128 v[248:251], v181 offset:4096
	v_add_u32_e32 v182, v227, v230
	s_waitcnt lgkmcnt(4)
	v_mfma_f32_32x32x16_bf16 v[116:131], v[84:87], v[148:151], v[116:131]
	ds_read_b128 v[84:87], v182
	s_waitcnt lgkmcnt(4)
	v_mfma_f32_32x32x16_bf16 v[100:115], v[236:239], v[144:147], v[100:115]
	ds_read_b128 v[236:239], v182 offset:4096
	v_add_u32_e32 v183, v227, v231
	s_waitcnt lgkmcnt(4)
	v_mfma_f32_32x32x16_bf16 v[116:131], v[240:243], v[144:147], v[116:131]
	ds_read_b128 v[240:243], v183
	s_waitcnt lgkmcnt(4)
	v_mfma_f32_32x32x16_bf16 v[100:115], v[244:247], v[140:143], v[100:115]
	ds_read_b128 v[244:247], v183 offset:4096
	s_waitcnt lgkmcnt(4)
	v_mfma_f32_32x32x16_bf16 v[116:131], v[248:251], v[140:143], v[116:131]
	s_waitcnt lgkmcnt(3)
	v_mfma_f32_32x32x16_bf16 v[100:115], v[84:87], v[136:139], v[100:115]
	s_waitcnt lgkmcnt(2)
	v_mfma_f32_32x32x16_bf16 v[116:131], v[236:239], v[136:139], v[116:131]
	s_waitcnt lgkmcnt(1)
	v_mfma_f32_32x32x16_bf16 v[100:115], v[240:243], v[132:135], v[100:115]
	s_waitcnt lgkmcnt(0)
	v_mfma_f32_32x32x16_bf16 v[116:131], v[244:247], v[132:135], v[116:131]
	ds_read_b64_tr_b16 v[236:237], v221 offset:0x0
	ds_read_b64_tr_b16 v[238:239], v221 offset:0x800
	ds_read_b64_tr_b16 v[240:241], v221 offset:0x1000
	ds_read_b64_tr_b16 v[242:243], v221 offset:0x1800
	ds_read_b64_tr_b16 v[244:245], v221 offset:0x2000
	ds_read_b64_tr_b16 v[246:247], v221 offset:0x2800
	ds_read_b64_tr_b16 v[248:249], v221 offset:0x3000
	ds_read_b64_tr_b16 v[250:251], v221 offset:0x3800
	s_nop 1
	s_cbranch_scc1 .LBB0_547
	v_add_u32_e32 v84, s53, v233
	v_add_u32_e32 v85, 0xffffff10, v84
	v_cmp_gt_u32_e32 vcc, 2.0, v85
	v_add_u32_e32 v85, 0xbffffef0, v84
	s_nop 3
	v_cndmask_b32_e32 v100, v212, v100, vcc
	v_cmp_lt_u32_e32 vcc, s82, v85
	v_add_u32_e32 v85, 0xbfffff0f, v84
	s_nop 0
	v_cndmask_b32_e32 v116, v212, v116, vcc
	v_cmp_lt_u32_e32 vcc, s82, v85
	v_add_u32_e32 v85, 0xbffffeef, v84
	s_nop 0
	v_cndmask_b32_e32 v101, v212, v101, vcc
	v_cmp_lt_u32_e32 vcc, s82, v85
	v_add_u32_e32 v85, 0xbfffff0e, v84
	s_nop 0
	v_cndmask_b32_e32 v117, v212, v117, vcc
	v_cmp_lt_u32_e32 vcc, s82, v85
	v_add_u32_e32 v85, 0xbffffeee, v84
	s_nop 0
	v_cndmask_b32_e32 v102, v212, v102, vcc
	v_cmp_lt_u32_e32 vcc, s82, v85
	v_add_u32_e32 v85, 0xbfffff0d, v84
	s_nop 0
	v_cndmask_b32_e32 v118, v212, v118, vcc
	v_cmp_lt_u32_e32 vcc, s82, v85
	v_add_u32_e32 v85, 0xbffffeed, v84
	s_nop 0
	v_cndmask_b32_e32 v103, v212, v103, vcc
	v_cmp_lt_u32_e32 vcc, s82, v85
	v_add_u32_e32 v85, 0xbfffff08, v84
	s_nop 0
	v_cndmask_b32_e32 v119, v212, v119, vcc
	v_cmp_lt_u32_e32 vcc, s82, v85
	v_add_u32_e32 v85, 0xbffffee8, v84
	s_nop 0
	v_cndmask_b32_e32 v104, v212, v104, vcc
	v_cmp_lt_u32_e32 vcc, s82, v85
	v_add_u32_e32 v85, 0xbfffff07, v84
	s_nop 0
	v_cndmask_b32_e32 v120, v212, v120, vcc
	v_cmp_lt_u32_e32 vcc, s82, v85
	v_add_u32_e32 v85, 0xbffffee7, v84
	s_nop 0
	v_cndmask_b32_e32 v105, v212, v105, vcc
	v_cmp_lt_u32_e32 vcc, s82, v85
	v_add_u32_e32 v85, 0xbfffff06, v84
	s_nop 0
	v_cndmask_b32_e32 v121, v212, v121, vcc
	v_cmp_lt_u32_e32 vcc, s82, v85
	v_add_u32_e32 v85, 0xbffffee6, v84
	s_nop 0
	v_cndmask_b32_e32 v106, v212, v106, vcc
	v_cmp_lt_u32_e32 vcc, s82, v85
	v_add_u32_e32 v85, 0xbfffff05, v84
	s_nop 0
	v_cndmask_b32_e32 v122, v212, v122, vcc
	v_cmp_lt_u32_e32 vcc, s82, v85
	v_add_u32_e32 v85, 0xbffffee5, v84
	s_nop 0
	v_cndmask_b32_e32 v107, v212, v107, vcc
	v_cmp_lt_u32_e32 vcc, s82, v85
	v_add_u32_e32 v85, 0xbfffff00, v84
	s_nop 0
	v_cndmask_b32_e32 v123, v212, v123, vcc
	v_cmp_lt_u32_e32 vcc, s82, v85
	v_add_u32_e32 v85, 0xbffffee0, v84
	s_nop 0
	v_cndmask_b32_e32 v108, v212, v108, vcc
	v_cmp_lt_u32_e32 vcc, s82, v85
	v_add_u32_e32 v85, 0xbffffeff, v84
	s_nop 0
	v_cndmask_b32_e32 v124, v212, v124, vcc
	v_cmp_lt_u32_e32 vcc, s82, v85
	v_add_u32_e32 v85, 0xbffffedf, v84
	s_nop 0
	v_cndmask_b32_e32 v109, v212, v109, vcc
	v_cmp_lt_u32_e32 vcc, s82, v85
	v_add_u32_e32 v85, 0xbffffefe, v84
	s_nop 0
	v_cndmask_b32_e32 v125, v212, v125, vcc
	v_cmp_lt_u32_e32 vcc, s82, v85
	v_add_u32_e32 v85, 0xbffffede, v84
	s_nop 0
	v_cndmask_b32_e32 v110, v212, v110, vcc
	v_cmp_lt_u32_e32 vcc, s82, v85
	v_add_u32_e32 v85, 0xbffffefd, v84
	s_nop 0
	v_cndmask_b32_e32 v126, v212, v126, vcc
	v_cmp_lt_u32_e32 vcc, s82, v85
	v_add_u32_e32 v85, 0xbffffedd, v84
	s_nop 0
	v_cndmask_b32_e32 v111, v212, v111, vcc
	v_cmp_lt_u32_e32 vcc, s82, v85
	v_add_u32_e32 v85, 0xbffffef8, v84
	s_nop 0
	v_cndmask_b32_e32 v127, v212, v127, vcc
	v_cmp_lt_u32_e32 vcc, s82, v85
	v_add_u32_e32 v85, 0xbffffed8, v84
	s_nop 0
	v_cndmask_b32_e32 v112, v212, v112, vcc
	v_cmp_lt_u32_e32 vcc, s82, v85
	v_add_u32_e32 v85, 0xbffffef7, v84
	s_nop 0
	v_cndmask_b32_e32 v128, v212, v128, vcc
	v_cmp_lt_u32_e32 vcc, s82, v85
	v_add_u32_e32 v85, 0xbffffed7, v84
	s_nop 0
	v_cndmask_b32_e32 v113, v212, v113, vcc
	v_cmp_lt_u32_e32 vcc, s82, v85
	v_add_u32_e32 v85, 0xbffffef6, v84
	s_nop 0
	v_cndmask_b32_e32 v129, v212, v129, vcc
	v_cmp_lt_u32_e32 vcc, s82, v85
	v_add_u32_e32 v85, 0xbffffed6, v84
	s_nop 0
	v_cndmask_b32_e32 v114, v212, v114, vcc
	v_cmp_lt_u32_e32 vcc, s82, v85
	v_add_u32_e32 v85, 0xbffffef5, v84
	v_add_u32_e32 v84, 0xbffffed5, v84
	v_cndmask_b32_e32 v130, v212, v130, vcc
	v_cmp_lt_u32_e32 vcc, s82, v85
	s_nop 1
	v_cndmask_b32_e32 v115, v212, v115, vcc
	v_cmp_lt_u32_e32 vcc, s82, v84
	s_nop 1
	v_cndmask_b32_e32 v131, v212, v131, vcc

.LBB0_554:
	v_exp_f32_e32 v100, v100
	v_exp_f32_e32 v101, v101
	v_exp_f32_e32 v102, v102
	v_exp_f32_e32 v103, v103
	v_exp_f32_e32 v182, v104
	v_add_f32_e32 v104, 0, v100
	v_exp_f32_e32 v183, v105
	v_add_f32_e32 v104, v101, v104
	v_exp_f32_e32 v184, v106
	v_add_f32_e32 v104, v102, v104
	v_exp_f32_e32 v107, v107
	v_add_f32_e32 v104, v103, v104
	v_exp_f32_e32 v108, v108
	v_add_f32_e32 v104, v182, v104
	v_exp_f32_e32 v109, v109
	v_add_f32_e32 v104, v183, v104
	v_exp_f32_e32 v110, v110
	v_add_f32_e32 v104, v184, v104
	v_exp_f32_e32 v111, v111
	v_add_f32_e32 v104, v107, v104
	v_exp_f32_e32 v112, v112
	v_add_f32_e32 v104, v108, v104
	v_exp_f32_e32 v113, v113
	v_add_f32_e32 v104, v109, v104
	v_exp_f32_e32 v114, v114
	v_add_f32_e32 v104, v110, v104
	v_exp_f32_e32 v115, v115
	v_add_f32_e32 v104, v111, v104
	v_exp_f32_e32 v180, v116
	v_add_f32_e32 v104, v112, v104
	v_exp_f32_e32 v181, v117
	v_add_f32_e32 v104, v113, v104
	v_exp_f32_e32 v118, v118
	v_add_f32_e32 v104, v114, v104
	v_exp_f32_e32 v119, v119
	v_add_f32_e32 v104, v115, v104
	v_exp_f32_e32 v120, v120
	v_add_f32_e32 v104, v180, v104
	v_exp_f32_e32 v121, v121
	v_add_f32_e32 v104, v181, v104
	v_exp_f32_e32 v122, v122
	v_add_f32_e32 v104, v118, v104
	v_exp_f32_e32 v123, v123
	v_add_f32_e32 v104, v119, v104
	v_exp_f32_e32 v124, v124
	v_add_f32_e32 v104, v120, v104
	v_exp_f32_e32 v125, v125
	v_add_f32_e32 v104, v121, v104
	v_exp_f32_e32 v126, v126
	v_add_f32_e32 v104, v122, v104
	v_exp_f32_e32 v127, v127
	v_add_f32_e32 v104, v123, v104
	v_exp_f32_e32 v128, v128
	v_add_f32_e32 v104, v124, v104
	v_exp_f32_e32 v129, v129
	v_add_f32_e32 v104, v125, v104
	v_exp_f32_e32 v130, v130
	v_add_f32_e32 v104, v126, v104
	v_exp_f32_e32 v131, v131
	v_add_f32_e32 v104, v127, v104
	v_add_f32_e32 v104, v128, v104
	v_add_f32_e32 v104, v129, v104
	v_add_f32_e32 v104, v130, v104
	v_add_f32_e32 v116, v131, v104
	v_mov_b32_e32 v117, v116
	v_cvt_pk_bf16_f32 v104, v100, v101
	v_cvt_pk_bf16_f32 v105, v102, v103
	v_cvt_pk_bf16_f32 v106, v182, v183
	v_cvt_pk_bf16_f32 v107, v184, v107
	v_cvt_pk_bf16_f32 v108, v108, v109
	v_cvt_pk_bf16_f32 v109, v110, v111
	v_cvt_pk_bf16_f32 v110, v112, v113
	v_cvt_pk_bf16_f32 v111, v114, v115
	v_cvt_pk_bf16_f32 v112, v180, v181
	v_cvt_pk_bf16_f32 v113, v118, v119
	v_cvt_pk_bf16_f32 v114, v120, v121
	v_cvt_pk_bf16_f32 v115, v122, v123
	v_cvt_pk_bf16_f32 v100, v124, v125
	v_cvt_pk_bf16_f32 v101, v126, v127
	v_cvt_pk_bf16_f32 v102, v128, v129
	v_cvt_pk_bf16_f32 v103, v130, v131
	s_nop 1
	v_permlane32_swap_b32_e32 v116, v117
	v_permlane32_swap_b32_e32 v104, v106
	v_permlane32_swap_b32_e32 v105, v107
	v_permlane32_swap_b32_e32 v108, v110
	v_permlane32_swap_b32_e32 v109, v111
	v_permlane32_swap_b32_e32 v112, v114
	v_permlane32_swap_b32_e32 v113, v115
	v_permlane32_swap_b32_e32 v100, v102
	v_permlane32_swap_b32_e32 v101, v103
	v_cmp_gt_f32_e32 vcc, 1.0, v235
	s_cbranch_vccz .LBB0_558
	s_and_saveexec_b64 s[10:11], s[38:39]
	ds_write_b32 v219, v235 offset:128
	s_or_b64 exec, exec, s[10:11]
	s_waitcnt lgkmcnt(0)
	ds_read_b128 v[118:121], v218 offset:224
	ds_read_b128 v[122:125], v218 offset:192
	ds_read_b128 v[126:129], v218 offset:160
	ds_read_b128 v[182:185], v218 offset:128
	s_waitcnt lgkmcnt(0)
	v_pk_mul_f32 v[18:19], v[18:19], v[120:121]
	v_pk_mul_f32 v[14:15], v[14:15], v[124:125]
	v_pk_mul_f32 v[10:11], v[10:11], v[128:129]
	v_pk_mul_f32 v[6:7], v[6:7], v[184:185]
	v_pk_mul_f32 v[16:17], v[16:17], v[118:119]
	v_pk_mul_f32 v[12:13], v[12:13], v[122:123]
	v_pk_mul_f32 v[8:9], v[8:9], v[126:127]
	v_pk_mul_f32 v[4:5], v[4:5], v[182:183]
	v_pk_mul_f32 v[66:67], v[66:67], v[120:121]
	v_pk_mul_f32 v[62:63], v[62:63], v[124:125]
	v_pk_mul_f32 v[58:59], v[58:59], v[128:129]
	v_pk_mul_f32 v[54:55], v[54:55], v[184:185]
	v_pk_mul_f32 v[64:65], v[64:65], v[118:119]
	v_pk_mul_f32 v[60:61], v[60:61], v[122:123]
	v_pk_mul_f32 v[56:57], v[56:57], v[126:127]
	v_pk_mul_f32 v[52:53], v[52:53], v[182:183]
	v_pk_mul_f32 v[34:35], v[34:35], v[120:121]
	v_pk_mul_f32 v[30:31], v[30:31], v[124:125]
	v_pk_mul_f32 v[26:27], v[26:27], v[128:129]
	v_pk_mul_f32 v[22:23], v[22:23], v[184:185]
	v_pk_mul_f32 v[32:33], v[32:33], v[118:119]
	v_pk_mul_f32 v[28:29], v[28:29], v[122:123]
	v_pk_mul_f32 v[24:25], v[24:25], v[126:127]
	v_pk_mul_f32 v[20:21], v[20:21], v[182:183]
	v_pk_mul_f32 v[50:51], v[50:51], v[120:121]
	v_pk_mul_f32 v[46:47], v[46:47], v[124:125]
	v_pk_mul_f32 v[42:43], v[42:43], v[128:129]
	v_pk_mul_f32 v[38:39], v[38:39], v[184:185]
	v_pk_mul_f32 v[48:49], v[48:49], v[118:119]
	v_pk_mul_f32 v[44:45], v[44:45], v[122:123]
	v_pk_mul_f32 v[40:41], v[40:41], v[126:127]
	v_pk_mul_f32 v[36:37], v[36:37], v[182:183]
.LBB0_558:
	v_add_f32_e32 v180, v116, v117
	v_fmac_f32_e32 v180, v222, v235
	ds_read_b64_tr_b16 v[116:117], v221 offset:0x200
	ds_read_b64_tr_b16 v[118:119], v221 offset:0xa00
	ds_read_b64_tr_b16 v[120:121], v221 offset:0x1200
	ds_read_b64_tr_b16 v[122:123], v221 offset:0x1a00
	ds_read_b64_tr_b16 v[124:125], v221 offset:0x2200
	ds_read_b64_tr_b16 v[126:127], v221 offset:0x2a00
	ds_read_b64_tr_b16 v[128:129], v221 offset:0x3200
	ds_read_b64_tr_b16 v[130:131], v221 offset:0x3a00
	s_waitcnt lgkmcnt(8)
	s_nop 0
	v_mfma_f32_32x32x16_bf16 v[4:19], v[104:107], v[236:239], v[4:19]
	v_mfma_f32_32x32x16_bf16 v[4:19], v[108:111], v[240:243], v[4:19]
	v_mfma_f32_32x32x16_bf16 v[4:19], v[112:115], v[244:247], v[4:19]
	v_mfma_f32_32x32x16_bf16 v[4:19], v[100:103], v[248:251], v[4:19]
	ds_read_b64_tr_b16 v[236:237], v221 offset:0x400
	ds_read_b64_tr_b16 v[238:239], v221 offset:0xc00
	ds_read_b64_tr_b16 v[240:241], v221 offset:0x1400
	ds_read_b64_tr_b16 v[242:243], v221 offset:0x1c00
	ds_read_b64_tr_b16 v[244:245], v221 offset:0x2400
	ds_read_b64_tr_b16 v[246:247], v221 offset:0x2c00
	ds_read_b64_tr_b16 v[248:249], v221 offset:0x3400
	ds_read_b64_tr_b16 v[250:251], v221 offset:0x3c00
	s_waitcnt lgkmcnt(8)
	v_mfma_f32_32x32x16_bf16 v[52:67], v[104:107], v[116:119], v[52:67]
	v_mfma_f32_32x32x16_bf16 v[52:67], v[108:111], v[120:123], v[52:67]
	v_mfma_f32_32x32x16_bf16 v[52:67], v[112:115], v[124:127], v[52:67]
	v_mfma_f32_32x32x16_bf16 v[52:67], v[100:103], v[128:131], v[52:67]
	ds_read_b64_tr_b16 v[116:117], v221 offset:0x600
	ds_read_b64_tr_b16 v[118:119], v221 offset:0xe00
	ds_read_b64_tr_b16 v[120:121], v221 offset:0x1600
	ds_read_b64_tr_b16 v[122:123], v221 offset:0x1e00
	ds_read_b64_tr_b16 v[124:125], v221 offset:0x2600
	ds_read_b64_tr_b16 v[126:127], v221 offset:0x2e00
	ds_read_b64_tr_b16 v[128:129], v221 offset:0x3600
	ds_read_b64_tr_b16 v[130:131], v221 offset:0x3e00
	s_waitcnt lgkmcnt(8)
	v_mfma_f32_32x32x16_bf16 v[20:35], v[104:107], v[236:239], v[20:35]
	v_mfma_f32_32x32x16_bf16 v[20:35], v[108:111], v[240:243], v[20:35]
	v_mfma_f32_32x32x16_bf16 v[20:35], v[112:115], v[244:247], v[20:35]
	v_mfma_f32_32x32x16_bf16 v[20:35], v[100:103], v[248:251], v[20:35]
	s_waitcnt lgkmcnt(0)
	v_mfma_f32_32x32x16_bf16 v[36:51], v[104:107], v[116:119], v[36:51]
	v_mov_b32_e32 v222, v180
	v_mfma_f32_32x32x16_bf16 v[36:51], v[108:111], v[120:123], v[36:51]
	v_mfma_f32_32x32x16_bf16 v[36:51], v[112:115], v[124:127], v[36:51]
	v_mfma_f32_32x32x16_bf16 v[36:51], v[100:103], v[128:131], v[36:51]
.LBB0_559:
	s_mov_b64 s[10:11], 0x4d680000
	s_mov_b32 m0, s21
	v_lshl_add_u64 v[100:101], v[198:199], 0, s[10:11]
	s_waitcnt vmcnt(0)
	s_waitcnt vmcnt(0) lgkmcnt(0)
	s_barrier
	global_load_lds_dwordx4 v[100:101], off
	v_lshl_add_u64 v[100:101], v[200:201], 0, s[10:11]
	s_mov_b32 m0, s15
	s_mov_b64 s[10:11], 0x2e604000
	global_load_lds_dwordx4 v[100:101], off
	v_lshl_add_u64 v[100:101], v[202:203], 0, s[92:93]
	s_mov_b32 m0, s33
	s_nop 0
	global_load_lds_dwordx4 v[100:101], off
	v_lshl_add_u64 v[100:101], v[204:205], 0, s[92:93]
	s_mov_b32 m0, s50
	s_nop 0
	global_load_lds_dwordx4 v[100:101], off
	v_lshl_add_u64 v[100:101], v[206:207], 0, s[10:11]
	s_mov_b32 m0, s51
	s_nop 0
	global_load_lds_dwordx4 v[100:101], off
	s_add_i32 s3, s24, 1
	s_cmp_gt_i32 s3, s14
	s_cbranch_scc1 .LBB0_543
	s_add_i32 s3, s24, 64
	s_cmp_le_i32 s3, s6
	v_add_u32_e32 v180, v226, v225
	v_xad_u32 v181, v225, 32, v226
	v_xad_u32 v182, v225, 64, v226
	ds_read_b128 v[116:119], v180 offset:49152
	ds_read_b128 v[236:239], v180 offset:57344
	ds_read_b128 v[240:243], v181 offset:49152
	ds_read_b128 v[244:247], v181 offset:57344
	ds_read_b128 v[248:251], v182 offset:49152
	s_waitcnt lgkmcnt(4)
	v_mfma_f32_32x32x16_bf16 v[100:115], v[116:119], v[176:179], v[84:99]
	ds_read_b128 v[116:119], v182 offset:57344
	v_xad_u32 v183, v225, s26, v226
	s_waitcnt lgkmcnt(4)
	v_mfma_f32_32x32x16_bf16 v[84:99], v[236:239], v[176:179], v[84:99]
	ds_read_b128 v[236:239], v183 offset:49152
	s_waitcnt lgkmcnt(4)
	v_mfma_f32_32x32x16_bf16 v[100:115], v[240:243], v[172:175], v[100:115]
	ds_read_b128 v[240:243], v183 offset:57344
	v_xad_u32 v180, v225, s57, v226
	s_waitcnt lgkmcnt(4)
	v_mfma_f32_32x32x16_bf16 v[84:99], v[244:247], v[172:175], v[84:99]
	ds_read_b128 v[244:247], v180 offset:49152
	s_waitcnt lgkmcnt(4)
	v_mfma_f32_32x32x16_bf16 v[100:115], v[248:251], v[168:171], v[100:115]
	ds_read_b128 v[248:251], v180 offset:57344
	v_xad_u32 v181, v225, s90, v226
	s_waitcnt lgkmcnt(4)
	v_mfma_f32_32x32x16_bf16 v[84:99], v[116:119], v[168:171], v[84:99]
	ds_read_b128 v[116:119], v181 offset:49152
	s_waitcnt lgkmcnt(4)
	v_mfma_f32_32x32x16_bf16 v[100:115], v[236:239], v[164:167], v[100:115]
	ds_read_b128 v[236:239], v181 offset:57344
	v_xad_u32 v182, v225, s56, v226
	s_waitcnt lgkmcnt(4)
	v_mfma_f32_32x32x16_bf16 v[84:99], v[240:243], v[164:167], v[84:99]
	ds_read_b128 v[240:243], v182 offset:49152
	s_waitcnt lgkmcnt(4)
	v_mfma_f32_32x32x16_bf16 v[100:115], v[244:247], v[160:163], v[100:115]
	ds_read_b128 v[244:247], v182 offset:57344
	v_xad_u32 v183, v225, s74, v226
	s_waitcnt lgkmcnt(4)
	v_mfma_f32_32x32x16_bf16 v[84:99], v[248:251], v[160:163], v[84:99]
	ds_read_b128 v[248:251], v183 offset:49152
	s_waitcnt lgkmcnt(4)
	v_mfma_f32_32x32x16_bf16 v[100:115], v[116:119], v[156:159], v[100:115]
	ds_read_b128 v[116:119], v183 offset:57344
	v_add_u32_e32 v180, v232, v228
	s_waitcnt lgkmcnt(4)
	v_mfma_f32_32x32x16_bf16 v[84:99], v[236:239], v[156:159], v[84:99]
	ds_read_b128 v[236:239], v180
	s_waitcnt lgkmcnt(4)
	v_mfma_f32_32x32x16_bf16 v[100:115], v[240:243], v[152:155], v[100:115]
	ds_read_b128 v[240:243], v180 offset:4096
	v_add_u32_e32 v181, v232, v229
	s_waitcnt lgkmcnt(4)
	v_mfma_f32_32x32x16_bf16 v[84:99], v[244:247], v[152:155], v[84:99]
	ds_read_b128 v[244:247], v181
	s_waitcnt lgkmcnt(4)
	v_mfma_f32_32x32x16_bf16 v[100:115], v[248:251], v[148:151], v[100:115]
	ds_read_b128 v[248:251], v181 offset:4096
	v_add_u32_e32 v182, v232, v230
	s_waitcnt lgkmcnt(4)
	v_mfma_f32_32x32x16_bf16 v[84:99], v[116:119], v[148:151], v[84:99]
	ds_read_b128 v[116:119], v182
	s_waitcnt lgkmcnt(4)
	v_mfma_f32_32x32x16_bf16 v[100:115], v[236:239], v[144:147], v[100:115]
	ds_read_b128 v[236:239], v182 offset:4096
	v_add_u32_e32 v183, v232, v231
	s_waitcnt lgkmcnt(4)
	v_mfma_f32_32x32x16_bf16 v[84:99], v[240:243], v[144:147], v[84:99]
	ds_read_b128 v[240:243], v183
	s_waitcnt lgkmcnt(4)
	v_mfma_f32_32x32x16_bf16 v[100:115], v[244:247], v[140:143], v[100:115]
	ds_read_b128 v[244:247], v183 offset:4096
	s_waitcnt lgkmcnt(4)
	v_mfma_f32_32x32x16_bf16 v[84:99], v[248:251], v[140:143], v[84:99]
	s_waitcnt lgkmcnt(3)
	v_mfma_f32_32x32x16_bf16 v[100:115], v[116:119], v[136:139], v[100:115]
	s_waitcnt lgkmcnt(2)
	v_mfma_f32_32x32x16_bf16 v[84:99], v[236:239], v[136:139], v[84:99]
	s_waitcnt lgkmcnt(1)
	v_mfma_f32_32x32x16_bf16 v[100:115], v[240:243], v[132:135], v[100:115]
	s_waitcnt lgkmcnt(0)
	v_mfma_f32_32x32x16_bf16 v[84:99], v[244:247], v[132:135], v[84:99]
	ds_read_b64_tr_b16 v[236:237], v221 offset:0x4000
	ds_read_b64_tr_b16 v[238:239], v221 offset:0x4800
	ds_read_b64_tr_b16 v[240:241], v221 offset:0x5000
	ds_read_b64_tr_b16 v[242:243], v221 offset:0x5800
	ds_read_b64_tr_b16 v[244:245], v221 offset:0x6000
	ds_read_b64_tr_b16 v[246:247], v221 offset:0x6800
	ds_read_b64_tr_b16 v[248:249], v221 offset:0x7000
	ds_read_b64_tr_b16 v[250:251], v221 offset:0x7800
	s_nop 1
	s_cbranch_scc1 .LBB0_562
	v_add_u32_e32 v116, s53, v233
	v_add_u32_e32 v117, 0xfffffed0, v116
	v_cmp_gt_u32_e32 vcc, 2.0, v117
	v_add_u32_e32 v117, 0xbffffeb0, v116
	s_nop 3
	v_cndmask_b32_e32 v100, v212, v100, vcc
	v_cmp_lt_u32_e32 vcc, s82, v117
	v_add_u32_e32 v117, 0xbffffecf, v116
	s_nop 0
	v_cndmask_b32_e32 v84, v212, v84, vcc
	v_cmp_lt_u32_e32 vcc, s82, v117
	v_add_u32_e32 v117, 0xbffffeaf, v116
	s_nop 0
	v_cndmask_b32_e32 v101, v212, v101, vcc
	v_cmp_lt_u32_e32 vcc, s82, v117
	v_add_u32_e32 v117, 0xbffffece, v116
	s_nop 0
	v_cndmask_b32_e32 v85, v212, v85, vcc
	v_cmp_lt_u32_e32 vcc, s82, v117
	v_add_u32_e32 v117, 0xbffffeae, v116
	s_nop 0
	v_cndmask_b32_e32 v102, v212, v102, vcc
	v_cmp_lt_u32_e32 vcc, s82, v117
	v_add_u32_e32 v117, 0xbffffecd, v116
	s_nop 0
	v_cndmask_b32_e32 v86, v212, v86, vcc
	v_cmp_lt_u32_e32 vcc, s82, v117
	v_add_u32_e32 v117, 0xbffffead, v116
	s_nop 0
	v_cndmask_b32_e32 v103, v212, v103, vcc
	v_cmp_lt_u32_e32 vcc, s82, v117
	v_add_u32_e32 v117, 0xbffffec8, v116
	s_nop 0
	v_cndmask_b32_e32 v87, v212, v87, vcc
	v_cmp_lt_u32_e32 vcc, s82, v117
	v_add_u32_e32 v117, 0xbffffea8, v116
	s_nop 0
	v_cndmask_b32_e32 v104, v212, v104, vcc
	v_cmp_lt_u32_e32 vcc, s82, v117
	v_add_u32_e32 v117, 0xbffffec7, v116
	s_nop 0
	v_cndmask_b32_e32 v88, v212, v88, vcc
	v_cmp_lt_u32_e32 vcc, s82, v117
	v_add_u32_e32 v117, 0xbffffea7, v116
	s_nop 0
	v_cndmask_b32_e32 v105, v212, v105, vcc
	v_cmp_lt_u32_e32 vcc, s82, v117
	v_add_u32_e32 v117, 0xbffffec6, v116
	s_nop 0
	v_cndmask_b32_e32 v89, v212, v89, vcc
	v_cmp_lt_u32_e32 vcc, s82, v117
	v_add_u32_e32 v117, 0xbffffea6, v116
	s_nop 0
	v_cndmask_b32_e32 v106, v212, v106, vcc
	v_cmp_lt_u32_e32 vcc, s82, v117
	v_add_u32_e32 v117, 0xbffffec5, v116
	s_nop 0
	v_cndmask_b32_e32 v90, v212, v90, vcc
	v_cmp_lt_u32_e32 vcc, s82, v117
	v_add_u32_e32 v117, 0xbffffea5, v116
	s_nop 0
	v_cndmask_b32_e32 v107, v212, v107, vcc
	v_cmp_lt_u32_e32 vcc, s82, v117
	v_add_u32_e32 v117, 0xbffffec0, v116
	s_nop 0
	v_cndmask_b32_e32 v91, v212, v91, vcc
	v_cmp_lt_u32_e32 vcc, s82, v117
	v_add_u32_e32 v117, 0xbffffea0, v116
	s_nop 0
	v_cndmask_b32_e32 v108, v212, v108, vcc
	v_cmp_lt_u32_e32 vcc, s82, v117
	v_add_u32_e32 v117, 0xbffffebf, v116
	s_nop 0
	v_cndmask_b32_e32 v92, v212, v92, vcc
	v_cmp_lt_u32_e32 vcc, s82, v117
	v_add_u32_e32 v117, 0xbffffe9f, v116
	s_nop 0
	v_cndmask_b32_e32 v109, v212, v109, vcc
	v_cmp_lt_u32_e32 vcc, s82, v117
	v_add_u32_e32 v117, 0xbffffebe, v116
	s_nop 0
	v_cndmask_b32_e32 v93, v212, v93, vcc
	v_cmp_lt_u32_e32 vcc, s82, v117
	v_add_u32_e32 v117, 0xbffffe9e, v116
	s_nop 0
	v_cndmask_b32_e32 v110, v212, v110, vcc
	v_cmp_lt_u32_e32 vcc, s82, v117
	v_add_u32_e32 v117, 0xbffffebd, v116
	s_nop 0
	v_cndmask_b32_e32 v94, v212, v94, vcc
	v_cmp_lt_u32_e32 vcc, s82, v117
	v_add_u32_e32 v117, 0xbffffe9d, v116
	s_nop 0
	v_cndmask_b32_e32 v111, v212, v111, vcc
	v_cmp_lt_u32_e32 vcc, s82, v117
	v_add_u32_e32 v117, 0xbffffeb8, v116
	s_nop 0
	v_cndmask_b32_e32 v95, v212, v95, vcc
	v_cmp_lt_u32_e32 vcc, s82, v117
	v_add_u32_e32 v117, 0xbffffe98, v116
	s_nop 0
	v_cndmask_b32_e32 v112, v212, v112, vcc
	v_cmp_lt_u32_e32 vcc, s82, v117
	v_add_u32_e32 v117, 0xbffffeb7, v116
	s_nop 0
	v_cndmask_b32_e32 v96, v212, v96, vcc
	v_cmp_lt_u32_e32 vcc, s82, v117
	v_add_u32_e32 v117, 0xbffffe97, v116
	s_nop 0
	v_cndmask_b32_e32 v113, v212, v113, vcc
	v_cmp_lt_u32_e32 vcc, s82, v117
	v_add_u32_e32 v117, 0xbffffeb6, v116
	s_nop 0
	v_cndmask_b32_e32 v97, v212, v97, vcc
	v_cmp_lt_u32_e32 vcc, s82, v117
	v_add_u32_e32 v117, 0xbffffe96, v116
	s_nop 0
	v_cndmask_b32_e32 v114, v212, v114, vcc
	v_cmp_lt_u32_e32 vcc, s82, v117
	v_add_u32_e32 v117, 0xbffffeb5, v116
	v_add_u32_e32 v116, 0xbffffe95, v116
	v_cndmask_b32_e32 v98, v212, v98, vcc
	v_cmp_lt_u32_e32 vcc, s82, v117
	s_nop 1
	v_cndmask_b32_e32 v115, v212, v115, vcc
	v_cmp_lt_u32_e32 vcc, s82, v116
	s_nop 1
	v_cndmask_b32_e32 v99, v212, v99, vcc
